# prep phase: weight transpose/convert rewritten (one 64-row x 64-k task per wave, coalesced column reads, each lane writes one full 128-byte line of the bf16 transposed weight; same mul + cvt_pk arithm
# speedup vs baseline: 1.0964x; 1.0221x over previous
.Ltr_begin:
	v_readlane_b32 s0, v253, 0
	v_readlane_b32 s1, v254, 54
	s_lshl_b32 s0, s0, 3
	s_lshr_b32 s1, s1, 6
	s_add_i32 s0, s0, s1
	s_cmpk_ge_u32 s0, 0x7d0
	s_cbranch_scc1 .Ltr_done
	s_cmpk_ge_u32 s0, 0x3e8
	s_cselect_b32 s28, 1, 0
	s_cselect_b32 s1, 0x3e8, 0
	s_sub_i32 s0, s0, s1
	s_cmpk_ge_u32 s0, 0x2c0
	s_cbranch_scc1 .Ltr_sel1
	s_lshr_b32 s22, s0, 4
	s_and_b32 s23, s0, 15
	s_branch .Ltr_win
.Ltr_sel1:
	s_cmpk_ge_u32 s0, 0x3c0
	s_cbranch_scc1 .Ltr_sel2
	s_sub_i32 s0, s0, 0x2c0
	s_lshr_b32 s22, s0, 4
	s_and_b32 s23, s0, 15
	s_branch .Ltr_wout
.Ltr_sel2:
	s_cmpk_ge_u32 s0, 0x3d8
	s_cbranch_scc1 .Ltr_sel3
	s_sub_i32 s0, s0, 0x3c0
	s_mul_i32 s22, s0, 11
	s_lshr_b32 s22, s22, 5
	s_mul_i32 s1, s22, 3
	s_sub_i32 s23, s0, s1
	s_branch .Ltr_wuq
.Ltr_sel3:
	s_sub_i32 s0, s0, 0x3d8
	s_lshr_b32 s22, s0, 1
	s_and_b32 s23, s0, 1
	s_branch .Ltr_wukv
.Ltr_win:
	s_lshl_b32 s24, s22, 6
	v_add_u32_e32 v10, s24, v221
	s_movk_i32 s25, 0x200
	s_cmp_lt_u32 s22, 2
	s_cbranch_scc1 .Ltr_win_d
	s_movk_i32 s25, 0x580
	s_cmp_lt_u32 s22, 4
	s_cbranch_scc1 .Ltr_win_d
	s_movk_i32 s25, 0xff00
	s_cmp_lt_u32 s22, 12
	s_cbranch_scc1 .Ltr_win_d
	s_movk_i32 s25, 0xff80
	s_cmp_lt_u32 s22, 26
	s_cbranch_scc1 .Ltr_win_d
	s_mov_b32 s25, 0
.Ltr_win_d:
	v_add_u32_e32 v11, s25, v10
	v_cmp_gt_u32_e32 vcc, 0xa60, v10
	s_mov_b64 s[44:45], vcc
	v_min_u32_e32 v11, 0xa5f, v11
	v_lshlrev_b32_e32 v11, 2, v11
	s_mul_i32 s0, s28, 0xa60000
	s_mul_i32 s1, s23, 0xa6000
	s_add_u32 s8, s52, s0
	s_addc_u32 s9, s53, 0
	s_add_u32 s8, s8, s1
	s_addc_u32 s9, s9, 0
	v_mul_u32_u24_e32 v12, 0x880, v10
	s_lshl_b32 s0, s23, 7
	v_add_u32_e32 v12, s0, v12
	v_readlane_b32 s78, v253, 7
	v_readlane_b32 s79, v253, 8
	s_mul_i32 s0, s28, 0x5d8000
	s_add_u32 s78, s78, s0
	s_addc_u32 s79, s79, 0
	s_mul_i32 s0, s28, 0x1000
	s_lshl_b32 s1, s23, 8
	s_add_u32 s20, s50, s0
	s_addc_u32 s21, s51, 0
	s_add_u32 s20, s20, s1
	s_addc_u32 s21, s21, 0
	global_load_dword v26, v11, s[8:9]
	s_add_u32 s8, s8, 0x2980
	s_addc_u32 s9, s9, 0
	global_load_dword v27, v11, s[8:9]
	s_add_u32 s8, s8, 0x2980
	s_addc_u32 s9, s9, 0
	global_load_dword v28, v11, s[8:9]
	s_add_u32 s8, s8, 0x2980
	s_addc_u32 s9, s9, 0
	global_load_dword v29, v11, s[8:9]
	s_add_u32 s8, s8, 0x2980
	s_addc_u32 s9, s9, 0
	global_load_dword v30, v11, s[8:9]
	s_add_u32 s8, s8, 0x2980
	s_addc_u32 s9, s9, 0
	global_load_dword v31, v11, s[8:9]
	s_add_u32 s8, s8, 0x2980
	s_addc_u32 s9, s9, 0
	global_load_dword v32, v11, s[8:9]
	s_add_u32 s8, s8, 0x2980
	s_addc_u32 s9, s9, 0
	global_load_dword v33, v11, s[8:9]
	s_add_u32 s8, s8, 0x2980
	s_addc_u32 s9, s9, 0
	global_load_dword v34, v11, s[8:9]
	s_add_u32 s8, s8, 0x2980
	s_addc_u32 s9, s9, 0
	global_load_dword v35, v11, s[8:9]
	s_add_u32 s8, s8, 0x2980
	s_addc_u32 s9, s9, 0
	global_load_dword v36, v11, s[8:9]
	s_add_u32 s8, s8, 0x2980
	s_addc_u32 s9, s9, 0
	global_load_dword v37, v11, s[8:9]
	s_add_u32 s8, s8, 0x2980
	s_addc_u32 s9, s9, 0
	global_load_dword v38, v11, s[8:9]
	s_add_u32 s8, s8, 0x2980
	s_addc_u32 s9, s9, 0
	global_load_dword v39, v11, s[8:9]
	s_add_u32 s8, s8, 0x2980
	s_addc_u32 s9, s9, 0
	global_load_dword v40, v11, s[8:9]
	s_add_u32 s8, s8, 0x2980
	s_addc_u32 s9, s9, 0
	global_load_dword v41, v11, s[8:9]
	s_add_u32 s8, s8, 0x2980
	s_addc_u32 s9, s9, 0
	global_load_dword v42, v11, s[8:9]
	s_add_u32 s8, s8, 0x2980
	s_addc_u32 s9, s9, 0
	global_load_dword v43, v11, s[8:9]
	s_add_u32 s8, s8, 0x2980
	s_addc_u32 s9, s9, 0
	global_load_dword v44, v11, s[8:9]
	s_add_u32 s8, s8, 0x2980
	s_addc_u32 s9, s9, 0
	global_load_dword v45, v11, s[8:9]
	s_add_u32 s8, s8, 0x2980
	s_addc_u32 s9, s9, 0
	global_load_dword v46, v11, s[8:9]
	s_add_u32 s8, s8, 0x2980
	s_addc_u32 s9, s9, 0
	global_load_dword v47, v11, s[8:9]
	s_add_u32 s8, s8, 0x2980
	s_addc_u32 s9, s9, 0
	global_load_dword v48, v11, s[8:9]
	s_add_u32 s8, s8, 0x2980
	s_addc_u32 s9, s9, 0
	global_load_dword v49, v11, s[8:9]
	s_add_u32 s8, s8, 0x2980
	s_addc_u32 s9, s9, 0
	global_load_dword v50, v11, s[8:9]
	s_add_u32 s8, s8, 0x2980
	s_addc_u32 s9, s9, 0
	global_load_dword v51, v11, s[8:9]
	s_add_u32 s8, s8, 0x2980
	s_addc_u32 s9, s9, 0
	global_load_dword v52, v11, s[8:9]
	s_add_u32 s8, s8, 0x2980
	s_addc_u32 s9, s9, 0
	global_load_dword v53, v11, s[8:9]
	s_add_u32 s8, s8, 0x2980
	s_addc_u32 s9, s9, 0
	global_load_dword v54, v11, s[8:9]
	s_add_u32 s8, s8, 0x2980
	s_addc_u32 s9, s9, 0
	global_load_dword v55, v11, s[8:9]
	s_add_u32 s8, s8, 0x2980
	s_addc_u32 s9, s9, 0
	global_load_dword v56, v11, s[8:9]
	s_add_u32 s8, s8, 0x2980
	s_addc_u32 s9, s9, 0
	global_load_dword v57, v11, s[8:9]
	s_add_u32 s8, s8, 0x2980
	s_addc_u32 s9, s9, 0
	s_load_dwordx8 s[88:95], s[20:21], 0x0
	s_waitcnt vmcnt(24)
	s_waitcnt lgkmcnt(0)
	v_mul_f32_e32 v26, s88, v26
	v_mul_f32_e32 v27, s89, v27
	v_mul_f32_e32 v28, s90, v28
	v_mul_f32_e32 v29, s91, v29
	v_mul_f32_e32 v30, s92, v30
	v_mul_f32_e32 v31, s93, v31
	v_mul_f32_e32 v32, s94, v32
	v_mul_f32_e32 v33, s95, v33
	v_cvt_pk_bf16_f32 v2, v26, v27
	v_cvt_pk_bf16_f32 v3, v28, v29
	v_cvt_pk_bf16_f32 v4, v30, v31
	v_cvt_pk_bf16_f32 v5, v32, v33
	v_cndmask_b32_e64 v2, 0, v2, s[44:45]
	v_cndmask_b32_e64 v3, 0, v3, s[44:45]
	v_cndmask_b32_e64 v4, 0, v4, s[44:45]
	v_cndmask_b32_e64 v5, 0, v5, s[44:45]
	global_store_dwordx4 v12, v[2:5], s[78:79] offset:0
	global_load_dword v58, v11, s[8:9]
	s_add_u32 s8, s8, 0x2980
	s_addc_u32 s9, s9, 0
	global_load_dword v59, v11, s[8:9]
	s_add_u32 s8, s8, 0x2980
	s_addc_u32 s9, s9, 0
	global_load_dword v60, v11, s[8:9]
	s_add_u32 s8, s8, 0x2980
	s_addc_u32 s9, s9, 0
	global_load_dword v61, v11, s[8:9]
	s_add_u32 s8, s8, 0x2980
	s_addc_u32 s9, s9, 0
	global_load_dword v62, v11, s[8:9]
	s_add_u32 s8, s8, 0x2980
	s_addc_u32 s9, s9, 0
	global_load_dword v63, v11, s[8:9]
	s_add_u32 s8, s8, 0x2980
	s_addc_u32 s9, s9, 0
	global_load_dword v64, v11, s[8:9]
	s_add_u32 s8, s8, 0x2980
	s_addc_u32 s9, s9, 0
	global_load_dword v65, v11, s[8:9]
	s_add_u32 s8, s8, 0x2980
	s_addc_u32 s9, s9, 0
	s_load_dwordx8 s[88:95], s[20:21], 0x20
	s_waitcnt vmcnt(25)
	s_waitcnt lgkmcnt(0)
	v_mul_f32_e32 v34, s88, v34
	v_mul_f32_e32 v35, s89, v35
	v_mul_f32_e32 v36, s90, v36
	v_mul_f32_e32 v37, s91, v37
	v_mul_f32_e32 v38, s92, v38
	v_mul_f32_e32 v39, s93, v39
	v_mul_f32_e32 v40, s94, v40
	v_mul_f32_e32 v41, s95, v41
	v_cvt_pk_bf16_f32 v2, v34, v35
	v_cvt_pk_bf16_f32 v3, v36, v37
	v_cvt_pk_bf16_f32 v4, v38, v39
	v_cvt_pk_bf16_f32 v5, v40, v41
	v_cndmask_b32_e64 v2, 0, v2, s[44:45]
	v_cndmask_b32_e64 v3, 0, v3, s[44:45]
	v_cndmask_b32_e64 v4, 0, v4, s[44:45]
	v_cndmask_b32_e64 v5, 0, v5, s[44:45]
	global_store_dwordx4 v12, v[2:5], s[78:79] offset:16
	global_load_dword v66, v11, s[8:9]
	s_add_u32 s8, s8, 0x2980
	s_addc_u32 s9, s9, 0
	global_load_dword v67, v11, s[8:9]
	s_add_u32 s8, s8, 0x2980
	s_addc_u32 s9, s9, 0
	global_load_dword v68, v11, s[8:9]
	s_add_u32 s8, s8, 0x2980
	s_addc_u32 s9, s9, 0
	global_load_dword v69, v11, s[8:9]
	s_add_u32 s8, s8, 0x2980
	s_addc_u32 s9, s9, 0
	global_load_dword v70, v11, s[8:9]
	s_add_u32 s8, s8, 0x2980
	s_addc_u32 s9, s9, 0
	global_load_dword v71, v11, s[8:9]
	s_add_u32 s8, s8, 0x2980
	s_addc_u32 s9, s9, 0
	global_load_dword v72, v11, s[8:9]
	s_add_u32 s8, s8, 0x2980
	s_addc_u32 s9, s9, 0
	global_load_dword v73, v11, s[8:9]
	s_add_u32 s8, s8, 0x2980
	s_addc_u32 s9, s9, 0
	s_load_dwordx8 s[88:95], s[20:21], 0x40
	s_waitcnt vmcnt(26)
	s_waitcnt lgkmcnt(0)
	v_mul_f32_e32 v42, s88, v42
	v_mul_f32_e32 v43, s89, v43
	v_mul_f32_e32 v44, s90, v44
	v_mul_f32_e32 v45, s91, v45
	v_mul_f32_e32 v46, s92, v46
	v_mul_f32_e32 v47, s93, v47
	v_mul_f32_e32 v48, s94, v48
	v_mul_f32_e32 v49, s95, v49
	v_cvt_pk_bf16_f32 v2, v42, v43
	v_cvt_pk_bf16_f32 v3, v44, v45
	v_cvt_pk_bf16_f32 v4, v46, v47
	v_cvt_pk_bf16_f32 v5, v48, v49
	v_cndmask_b32_e64 v2, 0, v2, s[44:45]
	v_cndmask_b32_e64 v3, 0, v3, s[44:45]
	v_cndmask_b32_e64 v4, 0, v4, s[44:45]
	v_cndmask_b32_e64 v5, 0, v5, s[44:45]
	global_store_dwordx4 v12, v[2:5], s[78:79] offset:32
	global_load_dword v74, v11, s[8:9]
	s_add_u32 s8, s8, 0x2980
	s_addc_u32 s9, s9, 0
	global_load_dword v75, v11, s[8:9]
	s_add_u32 s8, s8, 0x2980
	s_addc_u32 s9, s9, 0
	global_load_dword v76, v11, s[8:9]
	s_add_u32 s8, s8, 0x2980
	s_addc_u32 s9, s9, 0
	global_load_dword v77, v11, s[8:9]
	s_add_u32 s8, s8, 0x2980
	s_addc_u32 s9, s9, 0
	global_load_dword v78, v11, s[8:9]
	s_add_u32 s8, s8, 0x2980
	s_addc_u32 s9, s9, 0
	global_load_dword v79, v11, s[8:9]
	s_add_u32 s8, s8, 0x2980
	s_addc_u32 s9, s9, 0
	global_load_dword v80, v11, s[8:9]
	s_add_u32 s8, s8, 0x2980
	s_addc_u32 s9, s9, 0
	global_load_dword v81, v11, s[8:9]
	s_add_u32 s8, s8, 0x2980
	s_addc_u32 s9, s9, 0
	s_load_dwordx8 s[88:95], s[20:21], 0x60
	s_waitcnt vmcnt(27)
	s_waitcnt lgkmcnt(0)
	v_mul_f32_e32 v50, s88, v50
	v_mul_f32_e32 v51, s89, v51
	v_mul_f32_e32 v52, s90, v52
	v_mul_f32_e32 v53, s91, v53
	v_mul_f32_e32 v54, s92, v54
	v_mul_f32_e32 v55, s93, v55
	v_mul_f32_e32 v56, s94, v56
	v_mul_f32_e32 v57, s95, v57
	v_cvt_pk_bf16_f32 v2, v50, v51
	v_cvt_pk_bf16_f32 v3, v52, v53
	v_cvt_pk_bf16_f32 v4, v54, v55
	v_cvt_pk_bf16_f32 v5, v56, v57
	v_cndmask_b32_e64 v2, 0, v2, s[44:45]
	v_cndmask_b32_e64 v3, 0, v3, s[44:45]
	v_cndmask_b32_e64 v4, 0, v4, s[44:45]
	v_cndmask_b32_e64 v5, 0, v5, s[44:45]
	global_store_dwordx4 v12, v[2:5], s[78:79] offset:48
	global_load_dword v82, v11, s[8:9]
	s_add_u32 s8, s8, 0x2980
	s_addc_u32 s9, s9, 0
	global_load_dword v83, v11, s[8:9]
	s_add_u32 s8, s8, 0x2980
	s_addc_u32 s9, s9, 0
	global_load_dword v84, v11, s[8:9]
	s_add_u32 s8, s8, 0x2980
	s_addc_u32 s9, s9, 0
	global_load_dword v85, v11, s[8:9]
	s_add_u32 s8, s8, 0x2980
	s_addc_u32 s9, s9, 0
	global_load_dword v86, v11, s[8:9]
	s_add_u32 s8, s8, 0x2980
	s_addc_u32 s9, s9, 0
	global_load_dword v87, v11, s[8:9]
	s_add_u32 s8, s8, 0x2980
	s_addc_u32 s9, s9, 0
	global_load_dword v88, v11, s[8:9]
	s_add_u32 s8, s8, 0x2980
	s_addc_u32 s9, s9, 0
	global_load_dword v89, v11, s[8:9]
	s_add_u32 s8, s8, 0x2980
	s_addc_u32 s9, s9, 0
	s_load_dwordx8 s[88:95], s[20:21], 0x80
	s_waitcnt vmcnt(27)
	s_waitcnt lgkmcnt(0)
	v_mul_f32_e32 v58, s88, v58
	v_mul_f32_e32 v59, s89, v59
	v_mul_f32_e32 v60, s90, v60
	v_mul_f32_e32 v61, s91, v61
	v_mul_f32_e32 v62, s92, v62
	v_mul_f32_e32 v63, s93, v63
	v_mul_f32_e32 v64, s94, v64
	v_mul_f32_e32 v65, s95, v65
	v_cvt_pk_bf16_f32 v2, v58, v59
	v_cvt_pk_bf16_f32 v3, v60, v61
	v_cvt_pk_bf16_f32 v4, v62, v63
	v_cvt_pk_bf16_f32 v5, v64, v65
	v_cndmask_b32_e64 v2, 0, v2, s[44:45]
	v_cndmask_b32_e64 v3, 0, v3, s[44:45]
	v_cndmask_b32_e64 v4, 0, v4, s[44:45]
	v_cndmask_b32_e64 v5, 0, v5, s[44:45]
	global_store_dwordx4 v12, v[2:5], s[78:79] offset:64
	s_load_dwordx8 s[88:95], s[20:21], 0xa0
	s_waitcnt vmcnt(19)
	s_waitcnt lgkmcnt(0)
	v_mul_f32_e32 v66, s88, v66
	v_mul_f32_e32 v67, s89, v67
	v_mul_f32_e32 v68, s90, v68
	v_mul_f32_e32 v69, s91, v69
	v_mul_f32_e32 v70, s92, v70
	v_mul_f32_e32 v71, s93, v71
	v_mul_f32_e32 v72, s94, v72
	v_mul_f32_e32 v73, s95, v73
	v_cvt_pk_bf16_f32 v2, v66, v67
	v_cvt_pk_bf16_f32 v3, v68, v69
	v_cvt_pk_bf16_f32 v4, v70, v71
	v_cvt_pk_bf16_f32 v5, v72, v73
	v_cndmask_b32_e64 v2, 0, v2, s[44:45]
	v_cndmask_b32_e64 v3, 0, v3, s[44:45]
	v_cndmask_b32_e64 v4, 0, v4, s[44:45]
	v_cndmask_b32_e64 v5, 0, v5, s[44:45]
	global_store_dwordx4 v12, v[2:5], s[78:79] offset:80
	s_load_dwordx8 s[88:95], s[20:21], 0xc0
	s_waitcnt vmcnt(11)
	s_waitcnt lgkmcnt(0)
	v_mul_f32_e32 v74, s88, v74
	v_mul_f32_e32 v75, s89, v75
	v_mul_f32_e32 v76, s90, v76
	v_mul_f32_e32 v77, s91, v77
	v_mul_f32_e32 v78, s92, v78
	v_mul_f32_e32 v79, s93, v79
	v_mul_f32_e32 v80, s94, v80
	v_mul_f32_e32 v81, s95, v81
	v_cvt_pk_bf16_f32 v2, v74, v75
	v_cvt_pk_bf16_f32 v3, v76, v77
	v_cvt_pk_bf16_f32 v4, v78, v79
	v_cvt_pk_bf16_f32 v5, v80, v81
	v_cndmask_b32_e64 v2, 0, v2, s[44:45]
	v_cndmask_b32_e64 v3, 0, v3, s[44:45]
	v_cndmask_b32_e64 v4, 0, v4, s[44:45]
	v_cndmask_b32_e64 v5, 0, v5, s[44:45]
	global_store_dwordx4 v12, v[2:5], s[78:79] offset:96
	s_load_dwordx8 s[88:95], s[20:21], 0xe0
	s_waitcnt vmcnt(3)
	s_waitcnt lgkmcnt(0)
	v_mul_f32_e32 v82, s88, v82
	v_mul_f32_e32 v83, s89, v83
	v_mul_f32_e32 v84, s90, v84
	v_mul_f32_e32 v85, s91, v85
	v_mul_f32_e32 v86, s92, v86
	v_mul_f32_e32 v87, s93, v87
	v_mul_f32_e32 v88, s94, v88
	v_mul_f32_e32 v89, s95, v89
	v_cvt_pk_bf16_f32 v2, v82, v83
	v_cvt_pk_bf16_f32 v3, v84, v85
	v_cvt_pk_bf16_f32 v4, v86, v87
	v_cvt_pk_bf16_f32 v5, v88, v89
	v_cndmask_b32_e64 v2, 0, v2, s[44:45]
	v_cndmask_b32_e64 v3, 0, v3, s[44:45]
	v_cndmask_b32_e64 v4, 0, v4, s[44:45]
	v_cndmask_b32_e64 v5, 0, v5, s[44:45]
	global_store_dwordx4 v12, v[2:5], s[78:79] offset:112
	s_branch .Ltr_done
.Ltr_wout:
	s_lshl_b32 s24, s22, 6
	v_add_u32_e32 v10, s24, v221
	v_mov_b32_e32 v11, v10
	v_cmp_gt_u32_e32 vcc, 0x400, v10
	s_mov_b64 s[44:45], vcc
	v_min_u32_e32 v11, 0x3ff, v11
	v_lshlrev_b32_e32 v11, 2, v11
	s_mul_i32 s0, s28, 0x400000
	s_mul_i32 s1, s23, 0x40000
	s_add_u32 s8, s68, s0
	s_addc_u32 s9, s69, 0
	s_add_u32 s8, s8, s1
	s_addc_u32 s9, s9, 0
	v_mul_u32_u24_e32 v12, 0x880, v10
	s_lshl_b32 s0, s23, 7
	v_add_u32_e32 v12, s0, v12
	v_readlane_b32 s78, v253, 9
	v_readlane_b32 s79, v253, 10
	s_mul_i32 s0, s28, 0x220000
	s_add_u32 s78, s78, s0
	s_addc_u32 s79, s79, 0
	global_load_dword v26, v11, s[8:9]
	s_add_u32 s8, s8, 0x1000
	s_addc_u32 s9, s9, 0
	global_load_dword v27, v11, s[8:9]
	s_add_u32 s8, s8, 0x1000
	s_addc_u32 s9, s9, 0
	global_load_dword v28, v11, s[8:9]
	s_add_u32 s8, s8, 0x1000
	s_addc_u32 s9, s9, 0
	global_load_dword v29, v11, s[8:9]
	s_add_u32 s8, s8, 0x1000
	s_addc_u32 s9, s9, 0
	global_load_dword v30, v11, s[8:9]
	s_add_u32 s8, s8, 0x1000
	s_addc_u32 s9, s9, 0
	global_load_dword v31, v11, s[8:9]
	s_add_u32 s8, s8, 0x1000
	s_addc_u32 s9, s9, 0
	global_load_dword v32, v11, s[8:9]
	s_add_u32 s8, s8, 0x1000
	s_addc_u32 s9, s9, 0
	global_load_dword v33, v11, s[8:9]
	s_add_u32 s8, s8, 0x1000
	s_addc_u32 s9, s9, 0
	global_load_dword v34, v11, s[8:9]
	s_add_u32 s8, s8, 0x1000
	s_addc_u32 s9, s9, 0
	global_load_dword v35, v11, s[8:9]
	s_add_u32 s8, s8, 0x1000
	s_addc_u32 s9, s9, 0
	global_load_dword v36, v11, s[8:9]
	s_add_u32 s8, s8, 0x1000
	s_addc_u32 s9, s9, 0
	global_load_dword v37, v11, s[8:9]
	s_add_u32 s8, s8, 0x1000
	s_addc_u32 s9, s9, 0
	global_load_dword v38, v11, s[8:9]
	s_add_u32 s8, s8, 0x1000
	s_addc_u32 s9, s9, 0
	global_load_dword v39, v11, s[8:9]
	s_add_u32 s8, s8, 0x1000
	s_addc_u32 s9, s9, 0
	global_load_dword v40, v11, s[8:9]
	s_add_u32 s8, s8, 0x1000
	s_addc_u32 s9, s9, 0
	global_load_dword v41, v11, s[8:9]
	s_add_u32 s8, s8, 0x1000
	s_addc_u32 s9, s9, 0
	global_load_dword v42, v11, s[8:9]
	s_add_u32 s8, s8, 0x1000
	s_addc_u32 s9, s9, 0
	global_load_dword v43, v11, s[8:9]
	s_add_u32 s8, s8, 0x1000
	s_addc_u32 s9, s9, 0
	global_load_dword v44, v11, s[8:9]
	s_add_u32 s8, s8, 0x1000
	s_addc_u32 s9, s9, 0
	global_load_dword v45, v11, s[8:9]
	s_add_u32 s8, s8, 0x1000
	s_addc_u32 s9, s9, 0
	global_load_dword v46, v11, s[8:9]
	s_add_u32 s8, s8, 0x1000
	s_addc_u32 s9, s9, 0
	global_load_dword v47, v11, s[8:9]
	s_add_u32 s8, s8, 0x1000
	s_addc_u32 s9, s9, 0
	global_load_dword v48, v11, s[8:9]
	s_add_u32 s8, s8, 0x1000
	s_addc_u32 s9, s9, 0
	global_load_dword v49, v11, s[8:9]
	s_add_u32 s8, s8, 0x1000
	s_addc_u32 s9, s9, 0
	global_load_dword v50, v11, s[8:9]
	s_add_u32 s8, s8, 0x1000
	s_addc_u32 s9, s9, 0
	global_load_dword v51, v11, s[8:9]
	s_add_u32 s8, s8, 0x1000
	s_addc_u32 s9, s9, 0
	global_load_dword v52, v11, s[8:9]
	s_add_u32 s8, s8, 0x1000
	s_addc_u32 s9, s9, 0
	global_load_dword v53, v11, s[8:9]
	s_add_u32 s8, s8, 0x1000
	s_addc_u32 s9, s9, 0
	global_load_dword v54, v11, s[8:9]
	s_add_u32 s8, s8, 0x1000
	s_addc_u32 s9, s9, 0
	global_load_dword v55, v11, s[8:9]
	s_add_u32 s8, s8, 0x1000
	s_addc_u32 s9, s9, 0
	global_load_dword v56, v11, s[8:9]
	s_add_u32 s8, s8, 0x1000
	s_addc_u32 s9, s9, 0
	global_load_dword v57, v11, s[8:9]
	s_add_u32 s8, s8, 0x1000
	s_addc_u32 s9, s9, 0
	s_waitcnt vmcnt(24)
	v_cvt_pk_bf16_f32 v2, v26, v27
	v_cvt_pk_bf16_f32 v3, v28, v29
	v_cvt_pk_bf16_f32 v4, v30, v31
	v_cvt_pk_bf16_f32 v5, v32, v33
	v_cndmask_b32_e64 v2, 0, v2, s[44:45]
	v_cndmask_b32_e64 v3, 0, v3, s[44:45]
	v_cndmask_b32_e64 v4, 0, v4, s[44:45]
	v_cndmask_b32_e64 v5, 0, v5, s[44:45]
	global_store_dwordx4 v12, v[2:5], s[78:79] offset:0
	global_load_dword v58, v11, s[8:9]
	s_add_u32 s8, s8, 0x1000
	s_addc_u32 s9, s9, 0
	global_load_dword v59, v11, s[8:9]
	s_add_u32 s8, s8, 0x1000
	s_addc_u32 s9, s9, 0
	global_load_dword v60, v11, s[8:9]
	s_add_u32 s8, s8, 0x1000
	s_addc_u32 s9, s9, 0
	global_load_dword v61, v11, s[8:9]
	s_add_u32 s8, s8, 0x1000
	s_addc_u32 s9, s9, 0
	global_load_dword v62, v11, s[8:9]
	s_add_u32 s8, s8, 0x1000
	s_addc_u32 s9, s9, 0
	global_load_dword v63, v11, s[8:9]
	s_add_u32 s8, s8, 0x1000
	s_addc_u32 s9, s9, 0
	global_load_dword v64, v11, s[8:9]
	s_add_u32 s8, s8, 0x1000
	s_addc_u32 s9, s9, 0
	global_load_dword v65, v11, s[8:9]
	s_add_u32 s8, s8, 0x1000
	s_addc_u32 s9, s9, 0
	s_waitcnt vmcnt(25)
	v_cvt_pk_bf16_f32 v2, v34, v35
	v_cvt_pk_bf16_f32 v3, v36, v37
	v_cvt_pk_bf16_f32 v4, v38, v39
	v_cvt_pk_bf16_f32 v5, v40, v41
	v_cndmask_b32_e64 v2, 0, v2, s[44:45]
	v_cndmask_b32_e64 v3, 0, v3, s[44:45]
	v_cndmask_b32_e64 v4, 0, v4, s[44:45]
	v_cndmask_b32_e64 v5, 0, v5, s[44:45]
	global_store_dwordx4 v12, v[2:5], s[78:79] offset:16
	global_load_dword v66, v11, s[8:9]
	s_add_u32 s8, s8, 0x1000
	s_addc_u32 s9, s9, 0
	global_load_dword v67, v11, s[8:9]
	s_add_u32 s8, s8, 0x1000
	s_addc_u32 s9, s9, 0
	global_load_dword v68, v11, s[8:9]
	s_add_u32 s8, s8, 0x1000
	s_addc_u32 s9, s9, 0
	global_load_dword v69, v11, s[8:9]
	s_add_u32 s8, s8, 0x1000
	s_addc_u32 s9, s9, 0
	global_load_dword v70, v11, s[8:9]
	s_add_u32 s8, s8, 0x1000
	s_addc_u32 s9, s9, 0
	global_load_dword v71, v11, s[8:9]
	s_add_u32 s8, s8, 0x1000
	s_addc_u32 s9, s9, 0
	global_load_dword v72, v11, s[8:9]
	s_add_u32 s8, s8, 0x1000
	s_addc_u32 s9, s9, 0
	global_load_dword v73, v11, s[8:9]
	s_add_u32 s8, s8, 0x1000
	s_addc_u32 s9, s9, 0
	s_waitcnt vmcnt(26)
	v_cvt_pk_bf16_f32 v2, v42, v43
	v_cvt_pk_bf16_f32 v3, v44, v45
	v_cvt_pk_bf16_f32 v4, v46, v47
	v_cvt_pk_bf16_f32 v5, v48, v49
	v_cndmask_b32_e64 v2, 0, v2, s[44:45]
	v_cndmask_b32_e64 v3, 0, v3, s[44:45]
	v_cndmask_b32_e64 v4, 0, v4, s[44:45]
	v_cndmask_b32_e64 v5, 0, v5, s[44:45]
	global_store_dwordx4 v12, v[2:5], s[78:79] offset:32
	global_load_dword v74, v11, s[8:9]
	s_add_u32 s8, s8, 0x1000
	s_addc_u32 s9, s9, 0
	global_load_dword v75, v11, s[8:9]
	s_add_u32 s8, s8, 0x1000
	s_addc_u32 s9, s9, 0
	global_load_dword v76, v11, s[8:9]
	s_add_u32 s8, s8, 0x1000
	s_addc_u32 s9, s9, 0
	global_load_dword v77, v11, s[8:9]
	s_add_u32 s8, s8, 0x1000
	s_addc_u32 s9, s9, 0
	global_load_dword v78, v11, s[8:9]
	s_add_u32 s8, s8, 0x1000
	s_addc_u32 s9, s9, 0
	global_load_dword v79, v11, s[8:9]
	s_add_u32 s8, s8, 0x1000
	s_addc_u32 s9, s9, 0
	global_load_dword v80, v11, s[8:9]
	s_add_u32 s8, s8, 0x1000
	s_addc_u32 s9, s9, 0
	global_load_dword v81, v11, s[8:9]
	s_add_u32 s8, s8, 0x1000
	s_addc_u32 s9, s9, 0
	s_waitcnt vmcnt(27)
	v_cvt_pk_bf16_f32 v2, v50, v51
	v_cvt_pk_bf16_f32 v3, v52, v53
	v_cvt_pk_bf16_f32 v4, v54, v55
	v_cvt_pk_bf16_f32 v5, v56, v57
	v_cndmask_b32_e64 v2, 0, v2, s[44:45]
	v_cndmask_b32_e64 v3, 0, v3, s[44:45]
	v_cndmask_b32_e64 v4, 0, v4, s[44:45]
	v_cndmask_b32_e64 v5, 0, v5, s[44:45]
	global_store_dwordx4 v12, v[2:5], s[78:79] offset:48
	global_load_dword v82, v11, s[8:9]
	s_add_u32 s8, s8, 0x1000
	s_addc_u32 s9, s9, 0
	global_load_dword v83, v11, s[8:9]
	s_add_u32 s8, s8, 0x1000
	s_addc_u32 s9, s9, 0
	global_load_dword v84, v11, s[8:9]
	s_add_u32 s8, s8, 0x1000
	s_addc_u32 s9, s9, 0
	global_load_dword v85, v11, s[8:9]
	s_add_u32 s8, s8, 0x1000
	s_addc_u32 s9, s9, 0
	global_load_dword v86, v11, s[8:9]
	s_add_u32 s8, s8, 0x1000
	s_addc_u32 s9, s9, 0
	global_load_dword v87, v11, s[8:9]
	s_add_u32 s8, s8, 0x1000
	s_addc_u32 s9, s9, 0
	global_load_dword v88, v11, s[8:9]
	s_add_u32 s8, s8, 0x1000
	s_addc_u32 s9, s9, 0
	global_load_dword v89, v11, s[8:9]
	s_add_u32 s8, s8, 0x1000
	s_addc_u32 s9, s9, 0
	s_waitcnt vmcnt(27)
	v_cvt_pk_bf16_f32 v2, v58, v59
	v_cvt_pk_bf16_f32 v3, v60, v61
	v_cvt_pk_bf16_f32 v4, v62, v63
	v_cvt_pk_bf16_f32 v5, v64, v65
	v_cndmask_b32_e64 v2, 0, v2, s[44:45]
	v_cndmask_b32_e64 v3, 0, v3, s[44:45]
	v_cndmask_b32_e64 v4, 0, v4, s[44:45]
	v_cndmask_b32_e64 v5, 0, v5, s[44:45]
	global_store_dwordx4 v12, v[2:5], s[78:79] offset:64
	s_waitcnt vmcnt(19)
	v_cvt_pk_bf16_f32 v2, v66, v67
	v_cvt_pk_bf16_f32 v3, v68, v69
	v_cvt_pk_bf16_f32 v4, v70, v71
	v_cvt_pk_bf16_f32 v5, v72, v73
	v_cndmask_b32_e64 v2, 0, v2, s[44:45]
	v_cndmask_b32_e64 v3, 0, v3, s[44:45]
	v_cndmask_b32_e64 v4, 0, v4, s[44:45]
	v_cndmask_b32_e64 v5, 0, v5, s[44:45]
	global_store_dwordx4 v12, v[2:5], s[78:79] offset:80
	s_waitcnt vmcnt(11)
	v_cvt_pk_bf16_f32 v2, v74, v75
	v_cvt_pk_bf16_f32 v3, v76, v77
	v_cvt_pk_bf16_f32 v4, v78, v79
	v_cvt_pk_bf16_f32 v5, v80, v81
	v_cndmask_b32_e64 v2, 0, v2, s[44:45]
	v_cndmask_b32_e64 v3, 0, v3, s[44:45]
	v_cndmask_b32_e64 v4, 0, v4, s[44:45]
	v_cndmask_b32_e64 v5, 0, v5, s[44:45]
	global_store_dwordx4 v12, v[2:5], s[78:79] offset:96
	s_waitcnt vmcnt(3)
	v_cvt_pk_bf16_f32 v2, v82, v83
	v_cvt_pk_bf16_f32 v3, v84, v85
	v_cvt_pk_bf16_f32 v4, v86, v87
	v_cvt_pk_bf16_f32 v5, v88, v89
	v_cndmask_b32_e64 v2, 0, v2, s[44:45]
	v_cndmask_b32_e64 v3, 0, v3, s[44:45]
	v_cndmask_b32_e64 v4, 0, v4, s[44:45]
	v_cndmask_b32_e64 v5, 0, v5, s[44:45]
	global_store_dwordx4 v12, v[2:5], s[78:79] offset:112
	s_branch .Ltr_done
.Ltr_wuq:
	s_lshl_b32 s24, s22, 6
	v_add_u32_e32 v10, s24, v221
	v_mov_b32_e32 v11, v10
	v_cmp_gt_u32_e32 vcc, 0x180, v10
	s_mov_b64 s[44:45], vcc
	v_min_u32_e32 v11, 0x17f, v11
	v_lshlrev_b32_e32 v11, 2, v11
	s_mul_i32 s0, s28, 0x48000
	s_mul_i32 s1, s23, 0x18000
	s_add_u32 s8, s64, s0
	s_addc_u32 s9, s65, 0
	s_add_u32 s8, s8, s1
	s_addc_u32 s9, s9, 0
	v_mul_u32_u24_e32 v12, 0x180, v10
	s_lshl_b32 s0, s23, 7
	v_add_u32_e32 v12, s0, v12
	v_readlane_b32 s78, v253, 11
	v_readlane_b32 s79, v253, 12
	s_mul_i32 s0, s28, 0x30000
	s_add_u32 s78, s78, s0
	s_addc_u32 s79, s79, 0
	s_mul_i32 s0, s28, 0x300
	s_lshl_b32 s1, s23, 8
	s_add_u32 s20, s60, s0
	s_addc_u32 s21, s61, 0
	s_add_u32 s20, s20, s1
	s_addc_u32 s21, s21, 0
	global_load_dword v26, v11, s[8:9]
	s_add_u32 s8, s8, 0x600
	s_addc_u32 s9, s9, 0
	global_load_dword v27, v11, s[8:9]
	s_add_u32 s8, s8, 0x600
	s_addc_u32 s9, s9, 0
	global_load_dword v28, v11, s[8:9]
	s_add_u32 s8, s8, 0x600
	s_addc_u32 s9, s9, 0
	global_load_dword v29, v11, s[8:9]
	s_add_u32 s8, s8, 0x600
	s_addc_u32 s9, s9, 0
	global_load_dword v30, v11, s[8:9]
	s_add_u32 s8, s8, 0x600
	s_addc_u32 s9, s9, 0
	global_load_dword v31, v11, s[8:9]
	s_add_u32 s8, s8, 0x600
	s_addc_u32 s9, s9, 0
	global_load_dword v32, v11, s[8:9]
	s_add_u32 s8, s8, 0x600
	s_addc_u32 s9, s9, 0
	global_load_dword v33, v11, s[8:9]
	s_add_u32 s8, s8, 0x600
	s_addc_u32 s9, s9, 0
	global_load_dword v34, v11, s[8:9]
	s_add_u32 s8, s8, 0x600
	s_addc_u32 s9, s9, 0
	global_load_dword v35, v11, s[8:9]
	s_add_u32 s8, s8, 0x600
	s_addc_u32 s9, s9, 0
	global_load_dword v36, v11, s[8:9]
	s_add_u32 s8, s8, 0x600
	s_addc_u32 s9, s9, 0
	global_load_dword v37, v11, s[8:9]
	s_add_u32 s8, s8, 0x600
	s_addc_u32 s9, s9, 0
	global_load_dword v38, v11, s[8:9]
	s_add_u32 s8, s8, 0x600
	s_addc_u32 s9, s9, 0
	global_load_dword v39, v11, s[8:9]
	s_add_u32 s8, s8, 0x600
	s_addc_u32 s9, s9, 0
	global_load_dword v40, v11, s[8:9]
	s_add_u32 s8, s8, 0x600
	s_addc_u32 s9, s9, 0
	global_load_dword v41, v11, s[8:9]
	s_add_u32 s8, s8, 0x600
	s_addc_u32 s9, s9, 0
	global_load_dword v42, v11, s[8:9]
	s_add_u32 s8, s8, 0x600
	s_addc_u32 s9, s9, 0
	global_load_dword v43, v11, s[8:9]
	s_add_u32 s8, s8, 0x600
	s_addc_u32 s9, s9, 0
	global_load_dword v44, v11, s[8:9]
	s_add_u32 s8, s8, 0x600
	s_addc_u32 s9, s9, 0
	global_load_dword v45, v11, s[8:9]
	s_add_u32 s8, s8, 0x600
	s_addc_u32 s9, s9, 0
	global_load_dword v46, v11, s[8:9]
	s_add_u32 s8, s8, 0x600
	s_addc_u32 s9, s9, 0
	global_load_dword v47, v11, s[8:9]
	s_add_u32 s8, s8, 0x600
	s_addc_u32 s9, s9, 0
	global_load_dword v48, v11, s[8:9]
	s_add_u32 s8, s8, 0x600
	s_addc_u32 s9, s9, 0
	global_load_dword v49, v11, s[8:9]
	s_add_u32 s8, s8, 0x600
	s_addc_u32 s9, s9, 0
	global_load_dword v50, v11, s[8:9]
	s_add_u32 s8, s8, 0x600
	s_addc_u32 s9, s9, 0
	global_load_dword v51, v11, s[8:9]
	s_add_u32 s8, s8, 0x600
	s_addc_u32 s9, s9, 0
	global_load_dword v52, v11, s[8:9]
	s_add_u32 s8, s8, 0x600
	s_addc_u32 s9, s9, 0
	global_load_dword v53, v11, s[8:9]
	s_add_u32 s8, s8, 0x600
	s_addc_u32 s9, s9, 0
	global_load_dword v54, v11, s[8:9]
	s_add_u32 s8, s8, 0x600
	s_addc_u32 s9, s9, 0
	global_load_dword v55, v11, s[8:9]
	s_add_u32 s8, s8, 0x600
	s_addc_u32 s9, s9, 0
	global_load_dword v56, v11, s[8:9]
	s_add_u32 s8, s8, 0x600
	s_addc_u32 s9, s9, 0
	global_load_dword v57, v11, s[8:9]
	s_add_u32 s8, s8, 0x600
	s_addc_u32 s9, s9, 0
	s_load_dwordx8 s[88:95], s[20:21], 0x0
	s_waitcnt vmcnt(24)
	s_waitcnt lgkmcnt(0)
	v_mul_f32_e32 v26, s88, v26
	v_mul_f32_e32 v27, s89, v27
	v_mul_f32_e32 v28, s90, v28
	v_mul_f32_e32 v29, s91, v29
	v_mul_f32_e32 v30, s92, v30
	v_mul_f32_e32 v31, s93, v31
	v_mul_f32_e32 v32, s94, v32
	v_mul_f32_e32 v33, s95, v33
	v_cvt_pk_bf16_f32 v2, v26, v27
	v_cvt_pk_bf16_f32 v3, v28, v29
	v_cvt_pk_bf16_f32 v4, v30, v31
	v_cvt_pk_bf16_f32 v5, v32, v33
	v_cndmask_b32_e64 v2, 0, v2, s[44:45]
	v_cndmask_b32_e64 v3, 0, v3, s[44:45]
	v_cndmask_b32_e64 v4, 0, v4, s[44:45]
	v_cndmask_b32_e64 v5, 0, v5, s[44:45]
	global_store_dwordx4 v12, v[2:5], s[78:79] offset:0
	global_load_dword v58, v11, s[8:9]
	s_add_u32 s8, s8, 0x600
	s_addc_u32 s9, s9, 0
	global_load_dword v59, v11, s[8:9]
	s_add_u32 s8, s8, 0x600
	s_addc_u32 s9, s9, 0
	global_load_dword v60, v11, s[8:9]
	s_add_u32 s8, s8, 0x600
	s_addc_u32 s9, s9, 0
	global_load_dword v61, v11, s[8:9]
	s_add_u32 s8, s8, 0x600
	s_addc_u32 s9, s9, 0
	global_load_dword v62, v11, s[8:9]
	s_add_u32 s8, s8, 0x600
	s_addc_u32 s9, s9, 0
	global_load_dword v63, v11, s[8:9]
	s_add_u32 s8, s8, 0x600
	s_addc_u32 s9, s9, 0
	global_load_dword v64, v11, s[8:9]
	s_add_u32 s8, s8, 0x600
	s_addc_u32 s9, s9, 0
	global_load_dword v65, v11, s[8:9]
	s_add_u32 s8, s8, 0x600
	s_addc_u32 s9, s9, 0
	s_load_dwordx8 s[88:95], s[20:21], 0x20
	s_waitcnt vmcnt(25)
	s_waitcnt lgkmcnt(0)
	v_mul_f32_e32 v34, s88, v34
	v_mul_f32_e32 v35, s89, v35
	v_mul_f32_e32 v36, s90, v36
	v_mul_f32_e32 v37, s91, v37
	v_mul_f32_e32 v38, s92, v38
	v_mul_f32_e32 v39, s93, v39
	v_mul_f32_e32 v40, s94, v40
	v_mul_f32_e32 v41, s95, v41
	v_cvt_pk_bf16_f32 v2, v34, v35
	v_cvt_pk_bf16_f32 v3, v36, v37
	v_cvt_pk_bf16_f32 v4, v38, v39
	v_cvt_pk_bf16_f32 v5, v40, v41
	v_cndmask_b32_e64 v2, 0, v2, s[44:45]
	v_cndmask_b32_e64 v3, 0, v3, s[44:45]
	v_cndmask_b32_e64 v4, 0, v4, s[44:45]
	v_cndmask_b32_e64 v5, 0, v5, s[44:45]
	global_store_dwordx4 v12, v[2:5], s[78:79] offset:16
	global_load_dword v66, v11, s[8:9]
	s_add_u32 s8, s8, 0x600
	s_addc_u32 s9, s9, 0
	global_load_dword v67, v11, s[8:9]
	s_add_u32 s8, s8, 0x600
	s_addc_u32 s9, s9, 0
	global_load_dword v68, v11, s[8:9]
	s_add_u32 s8, s8, 0x600
	s_addc_u32 s9, s9, 0
	global_load_dword v69, v11, s[8:9]
	s_add_u32 s8, s8, 0x600
	s_addc_u32 s9, s9, 0
	global_load_dword v70, v11, s[8:9]
	s_add_u32 s8, s8, 0x600
	s_addc_u32 s9, s9, 0
	global_load_dword v71, v11, s[8:9]
	s_add_u32 s8, s8, 0x600
	s_addc_u32 s9, s9, 0
	global_load_dword v72, v11, s[8:9]
	s_add_u32 s8, s8, 0x600
	s_addc_u32 s9, s9, 0
	global_load_dword v73, v11, s[8:9]
	s_add_u32 s8, s8, 0x600
	s_addc_u32 s9, s9, 0
	s_load_dwordx8 s[88:95], s[20:21], 0x40
	s_waitcnt vmcnt(26)
	s_waitcnt lgkmcnt(0)
	v_mul_f32_e32 v42, s88, v42
	v_mul_f32_e32 v43, s89, v43
	v_mul_f32_e32 v44, s90, v44
	v_mul_f32_e32 v45, s91, v45
	v_mul_f32_e32 v46, s92, v46
	v_mul_f32_e32 v47, s93, v47
	v_mul_f32_e32 v48, s94, v48
	v_mul_f32_e32 v49, s95, v49
	v_cvt_pk_bf16_f32 v2, v42, v43
	v_cvt_pk_bf16_f32 v3, v44, v45
	v_cvt_pk_bf16_f32 v4, v46, v47
	v_cvt_pk_bf16_f32 v5, v48, v49
	v_cndmask_b32_e64 v2, 0, v2, s[44:45]
	v_cndmask_b32_e64 v3, 0, v3, s[44:45]
	v_cndmask_b32_e64 v4, 0, v4, s[44:45]
	v_cndmask_b32_e64 v5, 0, v5, s[44:45]
	global_store_dwordx4 v12, v[2:5], s[78:79] offset:32
	global_load_dword v74, v11, s[8:9]
	s_add_u32 s8, s8, 0x600
	s_addc_u32 s9, s9, 0
	global_load_dword v75, v11, s[8:9]
	s_add_u32 s8, s8, 0x600
	s_addc_u32 s9, s9, 0
	global_load_dword v76, v11, s[8:9]
	s_add_u32 s8, s8, 0x600
	s_addc_u32 s9, s9, 0
	global_load_dword v77, v11, s[8:9]
	s_add_u32 s8, s8, 0x600
	s_addc_u32 s9, s9, 0
	global_load_dword v78, v11, s[8:9]
	s_add_u32 s8, s8, 0x600
	s_addc_u32 s9, s9, 0
	global_load_dword v79, v11, s[8:9]
	s_add_u32 s8, s8, 0x600
	s_addc_u32 s9, s9, 0
	global_load_dword v80, v11, s[8:9]
	s_add_u32 s8, s8, 0x600
	s_addc_u32 s9, s9, 0
	global_load_dword v81, v11, s[8:9]
	s_add_u32 s8, s8, 0x600
	s_addc_u32 s9, s9, 0
	s_load_dwordx8 s[88:95], s[20:21], 0x60
	s_waitcnt vmcnt(27)
	s_waitcnt lgkmcnt(0)
	v_mul_f32_e32 v50, s88, v50
	v_mul_f32_e32 v51, s89, v51
	v_mul_f32_e32 v52, s90, v52
	v_mul_f32_e32 v53, s91, v53
	v_mul_f32_e32 v54, s92, v54
	v_mul_f32_e32 v55, s93, v55
	v_mul_f32_e32 v56, s94, v56
	v_mul_f32_e32 v57, s95, v57
	v_cvt_pk_bf16_f32 v2, v50, v51
	v_cvt_pk_bf16_f32 v3, v52, v53
	v_cvt_pk_bf16_f32 v4, v54, v55
	v_cvt_pk_bf16_f32 v5, v56, v57
	v_cndmask_b32_e64 v2, 0, v2, s[44:45]
	v_cndmask_b32_e64 v3, 0, v3, s[44:45]
	v_cndmask_b32_e64 v4, 0, v4, s[44:45]
	v_cndmask_b32_e64 v5, 0, v5, s[44:45]
	global_store_dwordx4 v12, v[2:5], s[78:79] offset:48
	global_load_dword v82, v11, s[8:9]
	s_add_u32 s8, s8, 0x600
	s_addc_u32 s9, s9, 0
	global_load_dword v83, v11, s[8:9]
	s_add_u32 s8, s8, 0x600
	s_addc_u32 s9, s9, 0
	global_load_dword v84, v11, s[8:9]
	s_add_u32 s8, s8, 0x600
	s_addc_u32 s9, s9, 0
	global_load_dword v85, v11, s[8:9]
	s_add_u32 s8, s8, 0x600
	s_addc_u32 s9, s9, 0
	global_load_dword v86, v11, s[8:9]
	s_add_u32 s8, s8, 0x600
	s_addc_u32 s9, s9, 0
	global_load_dword v87, v11, s[8:9]
	s_add_u32 s8, s8, 0x600
	s_addc_u32 s9, s9, 0
	global_load_dword v88, v11, s[8:9]
	s_add_u32 s8, s8, 0x600
	s_addc_u32 s9, s9, 0
	global_load_dword v89, v11, s[8:9]
	s_add_u32 s8, s8, 0x600
	s_addc_u32 s9, s9, 0
	s_load_dwordx8 s[88:95], s[20:21], 0x80
	s_waitcnt vmcnt(27)
	s_waitcnt lgkmcnt(0)
	v_mul_f32_e32 v58, s88, v58
	v_mul_f32_e32 v59, s89, v59
	v_mul_f32_e32 v60, s90, v60
	v_mul_f32_e32 v61, s91, v61
	v_mul_f32_e32 v62, s92, v62
	v_mul_f32_e32 v63, s93, v63
	v_mul_f32_e32 v64, s94, v64
	v_mul_f32_e32 v65, s95, v65
	v_cvt_pk_bf16_f32 v2, v58, v59
	v_cvt_pk_bf16_f32 v3, v60, v61
	v_cvt_pk_bf16_f32 v4, v62, v63
	v_cvt_pk_bf16_f32 v5, v64, v65
	v_cndmask_b32_e64 v2, 0, v2, s[44:45]
	v_cndmask_b32_e64 v3, 0, v3, s[44:45]
	v_cndmask_b32_e64 v4, 0, v4, s[44:45]
	v_cndmask_b32_e64 v5, 0, v5, s[44:45]
	global_store_dwordx4 v12, v[2:5], s[78:79] offset:64
	s_load_dwordx8 s[88:95], s[20:21], 0xa0
	s_waitcnt vmcnt(19)
	s_waitcnt lgkmcnt(0)
	v_mul_f32_e32 v66, s88, v66
	v_mul_f32_e32 v67, s89, v67
	v_mul_f32_e32 v68, s90, v68
	v_mul_f32_e32 v69, s91, v69
	v_mul_f32_e32 v70, s92, v70
	v_mul_f32_e32 v71, s93, v71
	v_mul_f32_e32 v72, s94, v72
	v_mul_f32_e32 v73, s95, v73
	v_cvt_pk_bf16_f32 v2, v66, v67
	v_cvt_pk_bf16_f32 v3, v68, v69
	v_cvt_pk_bf16_f32 v4, v70, v71
	v_cvt_pk_bf16_f32 v5, v72, v73
	v_cndmask_b32_e64 v2, 0, v2, s[44:45]
	v_cndmask_b32_e64 v3, 0, v3, s[44:45]
	v_cndmask_b32_e64 v4, 0, v4, s[44:45]
	v_cndmask_b32_e64 v5, 0, v5, s[44:45]
	global_store_dwordx4 v12, v[2:5], s[78:79] offset:80
	s_load_dwordx8 s[88:95], s[20:21], 0xc0
	s_waitcnt vmcnt(11)
	s_waitcnt lgkmcnt(0)
	v_mul_f32_e32 v74, s88, v74
	v_mul_f32_e32 v75, s89, v75
	v_mul_f32_e32 v76, s90, v76
	v_mul_f32_e32 v77, s91, v77
	v_mul_f32_e32 v78, s92, v78
	v_mul_f32_e32 v79, s93, v79
	v_mul_f32_e32 v80, s94, v80
	v_mul_f32_e32 v81, s95, v81
	v_cvt_pk_bf16_f32 v2, v74, v75
	v_cvt_pk_bf16_f32 v3, v76, v77
	v_cvt_pk_bf16_f32 v4, v78, v79
	v_cvt_pk_bf16_f32 v5, v80, v81
	v_cndmask_b32_e64 v2, 0, v2, s[44:45]
	v_cndmask_b32_e64 v3, 0, v3, s[44:45]
	v_cndmask_b32_e64 v4, 0, v4, s[44:45]
	v_cndmask_b32_e64 v5, 0, v5, s[44:45]
	global_store_dwordx4 v12, v[2:5], s[78:79] offset:96
	s_load_dwordx8 s[88:95], s[20:21], 0xe0
	s_waitcnt vmcnt(3)
	s_waitcnt lgkmcnt(0)
	v_mul_f32_e32 v82, s88, v82
	v_mul_f32_e32 v83, s89, v83
	v_mul_f32_e32 v84, s90, v84
	v_mul_f32_e32 v85, s91, v85
	v_mul_f32_e32 v86, s92, v86
	v_mul_f32_e32 v87, s93, v87
	v_mul_f32_e32 v88, s94, v88
	v_mul_f32_e32 v89, s95, v89
	v_cvt_pk_bf16_f32 v2, v82, v83
	v_cvt_pk_bf16_f32 v3, v84, v85
	v_cvt_pk_bf16_f32 v4, v86, v87
	v_cvt_pk_bf16_f32 v5, v88, v89
	v_cndmask_b32_e64 v2, 0, v2, s[44:45]
	v_cndmask_b32_e64 v3, 0, v3, s[44:45]
	v_cndmask_b32_e64 v4, 0, v4, s[44:45]
	v_cndmask_b32_e64 v5, 0, v5, s[44:45]
	global_store_dwordx4 v12, v[2:5], s[78:79] offset:112
	s_branch .Ltr_done
.Ltr_wukv:
	s_lshl_b32 s24, s22, 6
	v_add_u32_e32 v10, s24, v221
	v_mov_b32_e32 v11, v10
	v_cmp_gt_u32_e32 vcc, 0x200, v10
	s_mov_b64 s[44:45], vcc
	v_min_u32_e32 v11, 0x1ff, v11
	v_lshlrev_b32_e32 v11, 2, v11
	s_mul_i32 s0, s28, 0x40000
	s_mul_i32 s1, s23, 0x20000
	s_add_u32 s8, s66, s0
	s_addc_u32 s9, s67, 0
	s_add_u32 s8, s8, s1
	s_addc_u32 s9, s9, 0
	v_mul_u32_u24_e32 v12, 0x100, v10
	s_lshl_b32 s0, s23, 7
	v_add_u32_e32 v12, s0, v12
	v_readlane_b32 s78, v253, 13
	v_readlane_b32 s79, v253, 14
	s_mul_i32 s0, s28, 0x20000
	s_add_u32 s78, s78, s0
	s_addc_u32 s79, s79, 0
	s_mul_i32 s0, s28, 0x200
	s_lshl_b32 s1, s23, 8
	s_add_u32 s20, s62, s0
	s_addc_u32 s21, s63, 0
	s_add_u32 s20, s20, s1
	s_addc_u32 s21, s21, 0
	global_load_dword v26, v11, s[8:9]
	s_add_u32 s8, s8, 0x800
	s_addc_u32 s9, s9, 0
	global_load_dword v27, v11, s[8:9]
	s_add_u32 s8, s8, 0x800
	s_addc_u32 s9, s9, 0
	global_load_dword v28, v11, s[8:9]
	s_add_u32 s8, s8, 0x800
	s_addc_u32 s9, s9, 0
	global_load_dword v29, v11, s[8:9]
	s_add_u32 s8, s8, 0x800
	s_addc_u32 s9, s9, 0
	global_load_dword v30, v11, s[8:9]
	s_add_u32 s8, s8, 0x800
	s_addc_u32 s9, s9, 0
	global_load_dword v31, v11, s[8:9]
	s_add_u32 s8, s8, 0x800
	s_addc_u32 s9, s9, 0
	global_load_dword v32, v11, s[8:9]
	s_add_u32 s8, s8, 0x800
	s_addc_u32 s9, s9, 0
	global_load_dword v33, v11, s[8:9]
	s_add_u32 s8, s8, 0x800
	s_addc_u32 s9, s9, 0
	global_load_dword v34, v11, s[8:9]
	s_add_u32 s8, s8, 0x800
	s_addc_u32 s9, s9, 0
	global_load_dword v35, v11, s[8:9]
	s_add_u32 s8, s8, 0x800
	s_addc_u32 s9, s9, 0
	global_load_dword v36, v11, s[8:9]
	s_add_u32 s8, s8, 0x800
	s_addc_u32 s9, s9, 0
	global_load_dword v37, v11, s[8:9]
	s_add_u32 s8, s8, 0x800
	s_addc_u32 s9, s9, 0
	global_load_dword v38, v11, s[8:9]
	s_add_u32 s8, s8, 0x800
	s_addc_u32 s9, s9, 0
	global_load_dword v39, v11, s[8:9]
	s_add_u32 s8, s8, 0x800
	s_addc_u32 s9, s9, 0
	global_load_dword v40, v11, s[8:9]
	s_add_u32 s8, s8, 0x800
	s_addc_u32 s9, s9, 0
	global_load_dword v41, v11, s[8:9]
	s_add_u32 s8, s8, 0x800
	s_addc_u32 s9, s9, 0
	global_load_dword v42, v11, s[8:9]
	s_add_u32 s8, s8, 0x800
	s_addc_u32 s9, s9, 0
	global_load_dword v43, v11, s[8:9]
	s_add_u32 s8, s8, 0x800
	s_addc_u32 s9, s9, 0
	global_load_dword v44, v11, s[8:9]
	s_add_u32 s8, s8, 0x800
	s_addc_u32 s9, s9, 0
	global_load_dword v45, v11, s[8:9]
	s_add_u32 s8, s8, 0x800
	s_addc_u32 s9, s9, 0
	global_load_dword v46, v11, s[8:9]
	s_add_u32 s8, s8, 0x800
	s_addc_u32 s9, s9, 0
	global_load_dword v47, v11, s[8:9]
	s_add_u32 s8, s8, 0x800
	s_addc_u32 s9, s9, 0
	global_load_dword v48, v11, s[8:9]
	s_add_u32 s8, s8, 0x800
	s_addc_u32 s9, s9, 0
	global_load_dword v49, v11, s[8:9]
	s_add_u32 s8, s8, 0x800
	s_addc_u32 s9, s9, 0
	global_load_dword v50, v11, s[8:9]
	s_add_u32 s8, s8, 0x800
	s_addc_u32 s9, s9, 0
	global_load_dword v51, v11, s[8:9]
	s_add_u32 s8, s8, 0x800
	s_addc_u32 s9, s9, 0
	global_load_dword v52, v11, s[8:9]
	s_add_u32 s8, s8, 0x800
	s_addc_u32 s9, s9, 0
	global_load_dword v53, v11, s[8:9]
	s_add_u32 s8, s8, 0x800
	s_addc_u32 s9, s9, 0
	global_load_dword v54, v11, s[8:9]
	s_add_u32 s8, s8, 0x800
	s_addc_u32 s9, s9, 0
	global_load_dword v55, v11, s[8:9]
	s_add_u32 s8, s8, 0x800
	s_addc_u32 s9, s9, 0
	global_load_dword v56, v11, s[8:9]
	s_add_u32 s8, s8, 0x800
	s_addc_u32 s9, s9, 0
	global_load_dword v57, v11, s[8:9]
	s_add_u32 s8, s8, 0x800
	s_addc_u32 s9, s9, 0
	s_load_dwordx8 s[88:95], s[20:21], 0x0
	s_waitcnt vmcnt(24)
	s_waitcnt lgkmcnt(0)
	v_mul_f32_e32 v26, s88, v26
	v_mul_f32_e32 v27, s89, v27
	v_mul_f32_e32 v28, s90, v28
	v_mul_f32_e32 v29, s91, v29
	v_mul_f32_e32 v30, s92, v30
	v_mul_f32_e32 v31, s93, v31
	v_mul_f32_e32 v32, s94, v32
	v_mul_f32_e32 v33, s95, v33
	v_cvt_pk_bf16_f32 v2, v26, v27
	v_cvt_pk_bf16_f32 v3, v28, v29
	v_cvt_pk_bf16_f32 v4, v30, v31
	v_cvt_pk_bf16_f32 v5, v32, v33
	v_cndmask_b32_e64 v2, 0, v2, s[44:45]
	v_cndmask_b32_e64 v3, 0, v3, s[44:45]
	v_cndmask_b32_e64 v4, 0, v4, s[44:45]
	v_cndmask_b32_e64 v5, 0, v5, s[44:45]
	global_store_dwordx4 v12, v[2:5], s[78:79] offset:0
	global_load_dword v58, v11, s[8:9]
	s_add_u32 s8, s8, 0x800
	s_addc_u32 s9, s9, 0
	global_load_dword v59, v11, s[8:9]
	s_add_u32 s8, s8, 0x800
	s_addc_u32 s9, s9, 0
	global_load_dword v60, v11, s[8:9]
	s_add_u32 s8, s8, 0x800
	s_addc_u32 s9, s9, 0
	global_load_dword v61, v11, s[8:9]
	s_add_u32 s8, s8, 0x800
	s_addc_u32 s9, s9, 0
	global_load_dword v62, v11, s[8:9]
	s_add_u32 s8, s8, 0x800
	s_addc_u32 s9, s9, 0
	global_load_dword v63, v11, s[8:9]
	s_add_u32 s8, s8, 0x800
	s_addc_u32 s9, s9, 0
	global_load_dword v64, v11, s[8:9]
	s_add_u32 s8, s8, 0x800
	s_addc_u32 s9, s9, 0
	global_load_dword v65, v11, s[8:9]
	s_add_u32 s8, s8, 0x800
	s_addc_u32 s9, s9, 0
	s_load_dwordx8 s[88:95], s[20:21], 0x20
	s_waitcnt vmcnt(25)
	s_waitcnt lgkmcnt(0)
	v_mul_f32_e32 v34, s88, v34
	v_mul_f32_e32 v35, s89, v35
	v_mul_f32_e32 v36, s90, v36
	v_mul_f32_e32 v37, s91, v37
	v_mul_f32_e32 v38, s92, v38
	v_mul_f32_e32 v39, s93, v39
	v_mul_f32_e32 v40, s94, v40
	v_mul_f32_e32 v41, s95, v41
	v_cvt_pk_bf16_f32 v2, v34, v35
	v_cvt_pk_bf16_f32 v3, v36, v37
	v_cvt_pk_bf16_f32 v4, v38, v39
	v_cvt_pk_bf16_f32 v5, v40, v41
	v_cndmask_b32_e64 v2, 0, v2, s[44:45]
	v_cndmask_b32_e64 v3, 0, v3, s[44:45]
	v_cndmask_b32_e64 v4, 0, v4, s[44:45]
	v_cndmask_b32_e64 v5, 0, v5, s[44:45]
	global_store_dwordx4 v12, v[2:5], s[78:79] offset:16
	global_load_dword v66, v11, s[8:9]
	s_add_u32 s8, s8, 0x800
	s_addc_u32 s9, s9, 0
	global_load_dword v67, v11, s[8:9]
	s_add_u32 s8, s8, 0x800
	s_addc_u32 s9, s9, 0
	global_load_dword v68, v11, s[8:9]
	s_add_u32 s8, s8, 0x800
	s_addc_u32 s9, s9, 0
	global_load_dword v69, v11, s[8:9]
	s_add_u32 s8, s8, 0x800
	s_addc_u32 s9, s9, 0
	global_load_dword v70, v11, s[8:9]
	s_add_u32 s8, s8, 0x800
	s_addc_u32 s9, s9, 0
	global_load_dword v71, v11, s[8:9]
	s_add_u32 s8, s8, 0x800
	s_addc_u32 s9, s9, 0
	global_load_dword v72, v11, s[8:9]
	s_add_u32 s8, s8, 0x800
	s_addc_u32 s9, s9, 0
	global_load_dword v73, v11, s[8:9]
	s_add_u32 s8, s8, 0x800
	s_addc_u32 s9, s9, 0
	s_load_dwordx8 s[88:95], s[20:21], 0x40
	s_waitcnt vmcnt(26)
	s_waitcnt lgkmcnt(0)
	v_mul_f32_e32 v42, s88, v42
	v_mul_f32_e32 v43, s89, v43
	v_mul_f32_e32 v44, s90, v44
	v_mul_f32_e32 v45, s91, v45
	v_mul_f32_e32 v46, s92, v46
	v_mul_f32_e32 v47, s93, v47
	v_mul_f32_e32 v48, s94, v48
	v_mul_f32_e32 v49, s95, v49
	v_cvt_pk_bf16_f32 v2, v42, v43
	v_cvt_pk_bf16_f32 v3, v44, v45
	v_cvt_pk_bf16_f32 v4, v46, v47
	v_cvt_pk_bf16_f32 v5, v48, v49
	v_cndmask_b32_e64 v2, 0, v2, s[44:45]
	v_cndmask_b32_e64 v3, 0, v3, s[44:45]
	v_cndmask_b32_e64 v4, 0, v4, s[44:45]
	v_cndmask_b32_e64 v5, 0, v5, s[44:45]
	global_store_dwordx4 v12, v[2:5], s[78:79] offset:32
	global_load_dword v74, v11, s[8:9]
	s_add_u32 s8, s8, 0x800
	s_addc_u32 s9, s9, 0
	global_load_dword v75, v11, s[8:9]
	s_add_u32 s8, s8, 0x800
	s_addc_u32 s9, s9, 0
	global_load_dword v76, v11, s[8:9]
	s_add_u32 s8, s8, 0x800
	s_addc_u32 s9, s9, 0
	global_load_dword v77, v11, s[8:9]
	s_add_u32 s8, s8, 0x800
	s_addc_u32 s9, s9, 0
	global_load_dword v78, v11, s[8:9]
	s_add_u32 s8, s8, 0x800
	s_addc_u32 s9, s9, 0
	global_load_dword v79, v11, s[8:9]
	s_add_u32 s8, s8, 0x800
	s_addc_u32 s9, s9, 0
	global_load_dword v80, v11, s[8:9]
	s_add_u32 s8, s8, 0x800
	s_addc_u32 s9, s9, 0
	global_load_dword v81, v11, s[8:9]
	s_add_u32 s8, s8, 0x800
	s_addc_u32 s9, s9, 0
	s_load_dwordx8 s[88:95], s[20:21], 0x60
	s_waitcnt vmcnt(27)
	s_waitcnt lgkmcnt(0)
	v_mul_f32_e32 v50, s88, v50
	v_mul_f32_e32 v51, s89, v51
	v_mul_f32_e32 v52, s90, v52
	v_mul_f32_e32 v53, s91, v53
	v_mul_f32_e32 v54, s92, v54
	v_mul_f32_e32 v55, s93, v55
	v_mul_f32_e32 v56, s94, v56
	v_mul_f32_e32 v57, s95, v57
	v_cvt_pk_bf16_f32 v2, v50, v51
	v_cvt_pk_bf16_f32 v3, v52, v53
	v_cvt_pk_bf16_f32 v4, v54, v55
	v_cvt_pk_bf16_f32 v5, v56, v57
	v_cndmask_b32_e64 v2, 0, v2, s[44:45]
	v_cndmask_b32_e64 v3, 0, v3, s[44:45]
	v_cndmask_b32_e64 v4, 0, v4, s[44:45]
	v_cndmask_b32_e64 v5, 0, v5, s[44:45]
	global_store_dwordx4 v12, v[2:5], s[78:79] offset:48
	global_load_dword v82, v11, s[8:9]
	s_add_u32 s8, s8, 0x800
	s_addc_u32 s9, s9, 0
	global_load_dword v83, v11, s[8:9]
	s_add_u32 s8, s8, 0x800
	s_addc_u32 s9, s9, 0
	global_load_dword v84, v11, s[8:9]
	s_add_u32 s8, s8, 0x800
	s_addc_u32 s9, s9, 0
	global_load_dword v85, v11, s[8:9]
	s_add_u32 s8, s8, 0x800
	s_addc_u32 s9, s9, 0
	global_load_dword v86, v11, s[8:9]
	s_add_u32 s8, s8, 0x800
	s_addc_u32 s9, s9, 0
	global_load_dword v87, v11, s[8:9]
	s_add_u32 s8, s8, 0x800
	s_addc_u32 s9, s9, 0
	global_load_dword v88, v11, s[8:9]
	s_add_u32 s8, s8, 0x800
	s_addc_u32 s9, s9, 0
	global_load_dword v89, v11, s[8:9]
	s_add_u32 s8, s8, 0x800
	s_addc_u32 s9, s9, 0
	s_load_dwordx8 s[88:95], s[20:21], 0x80
	s_waitcnt vmcnt(27)
	s_waitcnt lgkmcnt(0)
	v_mul_f32_e32 v58, s88, v58
	v_mul_f32_e32 v59, s89, v59
	v_mul_f32_e32 v60, s90, v60
	v_mul_f32_e32 v61, s91, v61
	v_mul_f32_e32 v62, s92, v62
	v_mul_f32_e32 v63, s93, v63
	v_mul_f32_e32 v64, s94, v64
	v_mul_f32_e32 v65, s95, v65
	v_cvt_pk_bf16_f32 v2, v58, v59
	v_cvt_pk_bf16_f32 v3, v60, v61
	v_cvt_pk_bf16_f32 v4, v62, v63
	v_cvt_pk_bf16_f32 v5, v64, v65
	v_cndmask_b32_e64 v2, 0, v2, s[44:45]
	v_cndmask_b32_e64 v3, 0, v3, s[44:45]
	v_cndmask_b32_e64 v4, 0, v4, s[44:45]
	v_cndmask_b32_e64 v5, 0, v5, s[44:45]
	global_store_dwordx4 v12, v[2:5], s[78:79] offset:64
	s_load_dwordx8 s[88:95], s[20:21], 0xa0
	s_waitcnt vmcnt(19)
	s_waitcnt lgkmcnt(0)
	v_mul_f32_e32 v66, s88, v66
	v_mul_f32_e32 v67, s89, v67
	v_mul_f32_e32 v68, s90, v68
	v_mul_f32_e32 v69, s91, v69
	v_mul_f32_e32 v70, s92, v70
	v_mul_f32_e32 v71, s93, v71
	v_mul_f32_e32 v72, s94, v72
	v_mul_f32_e32 v73, s95, v73
	v_cvt_pk_bf16_f32 v2, v66, v67
	v_cvt_pk_bf16_f32 v3, v68, v69
	v_cvt_pk_bf16_f32 v4, v70, v71
	v_cvt_pk_bf16_f32 v5, v72, v73
	v_cndmask_b32_e64 v2, 0, v2, s[44:45]
	v_cndmask_b32_e64 v3, 0, v3, s[44:45]
	v_cndmask_b32_e64 v4, 0, v4, s[44:45]
	v_cndmask_b32_e64 v5, 0, v5, s[44:45]
	global_store_dwordx4 v12, v[2:5], s[78:79] offset:80
	s_load_dwordx8 s[88:95], s[20:21], 0xc0
	s_waitcnt vmcnt(11)
	s_waitcnt lgkmcnt(0)
	v_mul_f32_e32 v74, s88, v74
	v_mul_f32_e32 v75, s89, v75
	v_mul_f32_e32 v76, s90, v76
	v_mul_f32_e32 v77, s91, v77
	v_mul_f32_e32 v78, s92, v78
	v_mul_f32_e32 v79, s93, v79
	v_mul_f32_e32 v80, s94, v80
	v_mul_f32_e32 v81, s95, v81
	v_cvt_pk_bf16_f32 v2, v74, v75
	v_cvt_pk_bf16_f32 v3, v76, v77
	v_cvt_pk_bf16_f32 v4, v78, v79
	v_cvt_pk_bf16_f32 v5, v80, v81
	v_cndmask_b32_e64 v2, 0, v2, s[44:45]
	v_cndmask_b32_e64 v3, 0, v3, s[44:45]
	v_cndmask_b32_e64 v4, 0, v4, s[44:45]
	v_cndmask_b32_e64 v5, 0, v5, s[44:45]
	global_store_dwordx4 v12, v[2:5], s[78:79] offset:96
	s_load_dwordx8 s[88:95], s[20:21], 0xe0
	s_waitcnt vmcnt(3)
	s_waitcnt lgkmcnt(0)
	v_mul_f32_e32 v82, s88, v82
	v_mul_f32_e32 v83, s89, v83
	v_mul_f32_e32 v84, s90, v84
	v_mul_f32_e32 v85, s91, v85
	v_mul_f32_e32 v86, s92, v86
	v_mul_f32_e32 v87, s93, v87
	v_mul_f32_e32 v88, s94, v88
	v_mul_f32_e32 v89, s95, v89
	v_cvt_pk_bf16_f32 v2, v82, v83
	v_cvt_pk_bf16_f32 v3, v84, v85
	v_cvt_pk_bf16_f32 v4, v86, v87
	v_cvt_pk_bf16_f32 v5, v88, v89
	v_cndmask_b32_e64 v2, 0, v2, s[44:45]
	v_cndmask_b32_e64 v3, 0, v3, s[44:45]
	v_cndmask_b32_e64 v4, 0, v4, s[44:45]
	v_cndmask_b32_e64 v5, 0, v5, s[44:45]
	global_store_dwordx4 v12, v[2:5], s[78:79] offset:112
	s_branch .Ltr_done
.Ltr_done:
	s_branch .LBB0_514
.LBB0_514:
	s_mov_b64 s[0:1], 0x8000
	v_cmp_gt_i64_e32 vcc, s[0:1], v[6:7]
	s_mul_hi_u32 s1, s18, s77
	s_mul_i32 s0, s18, s77
	s_and_saveexec_b64 s[42:43], vcc
	s_cbranch_execz .LBB0_521
	v_readlane_b32 s8, v253, 15
	v_readlane_b32 s9, v253, 16
	s_lshl_b64 s[44:45], s[0:1], 3
	s_mov_b64 s[90:91], 0
	v_lshl_add_u64 v[2:3], v[6:7], 3, s[8:9]
	v_mov_b64_e32 v[4:5], v[6:7]
	s_branch .LBB0_517
